# diff attention unit epilogue: sub-LN gamma preloaded once per layer into registers; 16 serialized load+store-ack round trips per unit removed
# speedup vs baseline: 1.0093x; 1.0093x over previous
; __device__ __forceinline__ int cur_lane() { int l; asm volatile("v_mbcnt_lo_u32_b32 %0, -1, 0\n\tv_mbcnt_hi_u32_b32 %0, -1, %0" : "=v"(l)); return l; }
; __device__ __forceinline__ void diff_unit(ALDS unsigned char* ring, const int wid, int lane, const bf16_t* qkv, bf16_t* ymix, const int u, const float lam, const float post, const float* subg, const bool pre, const int u_next) {
;     ...
;             for (int rq = 0; rq < 4; ++rq) { const f32x4 gv = *(const f32x4*)(subg + 32 * db + 8 * rq + 4 * hi);
; __global__ void __launch_bounds__(NWAVES * 64, 2) fwd_megakernel(Args args) {
;     ...
;             const float lam_init = args.lam_init[l], lam = LAMV[l];
;             const float* subg = args.in[5] + (size_t)l * 128; const float* sink = args.in[6] + (size_t)l * 8;
;             for (int u = vcu; u < 2048; u += G) att::diff_unit(lds, wave, cur_lane(), QKV, YM, u, lam, 1.0f - lam_init, subg, u != vcu, (u + G < 2048) ? u + G : -1);
.LBB0_763:
	s_or_b64 exec, exec, s[40:41]
	v_readlane_b32 s0, v254, 26
	v_readlane_b32 s1, v254, 27
	s_andn2_b64 vcc, exec, s[0:1]
	s_waitcnt lgkmcnt(0)
	s_barrier
	s_cbranch_vccnz .LBB0_795
	v_readlane_b32 s4, v255, 32
	v_readlane_b32 s5, v255, 33
	s_lshl_b64 s[0:1], s[4:5], 9
	v_readlane_b32 s8, v255, 18
	v_readlane_b32 s9, v255, 19
	s_add_u32 s42, s8, s0
	s_addc_u32 s43, s9, s1
	v_mbcnt_lo_u32_b32 v248, -1, 0
	v_mbcnt_hi_u32_b32 v248, -1, v248
	v_ashrrev_i32_e32 v248, 3, v248
	v_and_b32_e32 v248, -4, v248
	v_lshlrev_b32_e32 v248, 2, v248
	global_load_dwordx4 v[178:181], v248, s[42:43]
	global_load_dwordx4 v[182:185], v248, s[42:43] offset:32
	global_load_dwordx4 v[186:189], v248, s[42:43] offset:64
	global_load_dwordx4 v[190:193], v248, s[42:43] offset:96
	global_load_dwordx4 v[194:197], v248, s[42:43] offset:128
	global_load_dwordx4 v[198:201], v248, s[42:43] offset:160
	global_load_dwordx4 v[202:205], v248, s[42:43] offset:192
	global_load_dwordx4 v[210:213], v248, s[42:43] offset:224
	global_load_dwordx4 v[214:217], v248, s[42:43] offset:256
	global_load_dwordx4 v[218:221], v248, s[42:43] offset:288
	global_load_dwordx4 v[222:225], v248, s[42:43] offset:320
	global_load_dwordx4 v[226:229], v248, s[42:43] offset:352
	global_load_dwordx4 v[232:235], v248, s[42:43] offset:384
	global_load_dwordx4 v[236:239], v248, s[42:43] offset:416
	global_load_dwordx4 v[240:243], v248, s[42:43] offset:448
	global_load_dwordx4 v[244:247], v248, s[42:43] offset:480
	s_lshl_b64 s[0:1], s[4:5], 2
	v_readlane_b32 s4, v253, 10
	v_readlane_b32 s5, v253, 11
	s_add_u32 s4, s4, s0
	s_addc_u32 s5, s5, s1
	v_readlane_b32 s10, v255, 20
	v_readlane_b32 s11, v255, 21
	s_nop 0
	global_load_dword v146, v1, s[4:5]
	v_readlane_b32 s4, v253, 16
	v_readlane_b32 s5, v253, 17
	s_add_u32 s0, s4, s0
	s_addc_u32 s1, s5, s1
	s_load_dword s0, s[0:1], 0xf8
	s_waitcnt lgkmcnt(0)
	v_sub_f32_e64 v148, 1.0, s0
	v_readlane_b32 s0, v253, 8
	v_readlane_b32 s1, v253, 9
	s_waitcnt vmcnt(0)
	v_mov_b32_e32 v147, v146
	s_branch .LBB0_766

; __device__ __forceinline__ void diff_unit(ALDS unsigned char* ring, const int wid, int lane, const bf16_t* qkv, bf16_t* ymix, const int u, const float lam, const float post, const float* subg, const bool pre, const int u_next) {
;     ...
;     if (comp == 0) {
;         float ss = 0.f;
; #pragma unroll
;         for (int db = 0; db < 4; ++db)
; #pragma unroll
;             for (int rq = 0; rq < 4; ++rq) { const f32x4 o2 = X[(db * 4 + rq) * 64 + lane];
; #pragma unroll
;                 for (int e = 0; e < 4; ++e) { const float d = o[db][4 * rq + e] * inv - lam * o2[e]; o[db][4 * rq + e] = d; ss += d * d; } }
.LBB0_781:
	v_readlane_b32 s4, v253, 12
	s_waitcnt lgkmcnt(0)
	s_barrier
	v_readlane_b32 s5, v253, 13
	s_andn2_b64 vcc, exec, s[4:5]
	s_cbranch_vccnz .LBB0_765
	ds_read_b128 v[92:95], v66
	ds_read_b128 v[98:101], v66 offset:1024
	ds_read_b128 v[102:105], v66 offset:2048
	ds_read_b128 v[106:109], v66 offset:3072
	ds_read_b128 v[110:113], v66 offset:4096
	ds_read_b128 v[114:117], v66 offset:5120
	ds_read_b128 v[118:121], v66 offset:6144
	ds_read_b128 v[122:125], v66 offset:7168
	ds_read_b128 v[126:129], v66 offset:8192
	ds_read_b128 v[130:133], v66 offset:9216
	ds_read_b128 v[134:137], v66 offset:10240
	ds_read_b128 v[138:141], v66 offset:11264
	ds_read_b128 v[82:85], v66 offset:12288
	ds_read_b128 v[78:81], v66 offset:13312
	ds_read_b128 v[74:77], v66 offset:14336
	ds_read_b128 v[70:73], v66 offset:15360
	s_waitcnt lgkmcnt(14)
	v_pk_mul_f32 v[90:91], v[146:147], v[94:95]
	v_or_b32_e32 v66, s1, v150
	v_pk_fma_f32 v[90:91], v[52:53], v[0:1], v[90:91] op_sel_hi:[1,0,1] neg_lo:[0,0,1] neg_hi:[0,0,1]
	v_pk_mul_f32 v[52:53], v[146:147], v[92:93]
	v_mov_b32_e32 v67, s45
	v_pk_fma_f32 v[92:93], v[50:51], v[0:1], v[52:53] op_sel_hi:[1,0,1] neg_lo:[0,0,1] neg_hi:[0,0,1]
	v_mul_f32_e32 v52, v91, v91
	v_mul_f32_e32 v50, v93, v93
	v_pk_fma_f32 v[50:51], v[92:93], v[92:93], v[50:51] op_sel_hi:[1,1,0]
	v_ashrrev_i32_e32 v68, 3, v149
	v_pk_fma_f32 v[50:51], v[90:91], v[90:91], v[50:51]
	v_lshlrev_b64 v[66:67], 11, v[66:67]
	v_pk_add_f32 v[50:51], v[52:53], v[50:51] op_sel_hi:[0,1]
	v_pk_mul_f32 v[52:53], v[146:147], v[100:101]
	v_and_b32_e32 v68, -4, v68
	v_pk_fma_f32 v[96:97], v[56:57], v[0:1], v[52:53] op_sel_hi:[1,0,1] neg_lo:[0,0,1] neg_hi:[0,0,1]
	v_pk_mul_f32 v[52:53], v[146:147], v[98:99]
	v_lshl_add_u64 v[66:67], s[96:97], 0, v[66:67]
	v_pk_fma_f32 v[98:99], v[54:55], v[0:1], v[52:53] op_sel_hi:[1,0,1] neg_lo:[0,0,1] neg_hi:[0,0,1]
	v_ashrrev_i32_e32 v69, 31, v68
	v_pk_fma_f32 v[50:51], v[98:99], v[98:99], v[50:51]
	v_mul_f32_e32 v52, v99, v99
	v_pk_add_f32 v[50:51], v[52:53], v[50:51] op_sel_hi:[0,1]
	v_pk_fma_f32 v[50:51], v[96:97], v[96:97], v[50:51]
	v_mul_f32_e32 v52, v97, v97
	v_pk_add_f32 v[50:51], v[52:53], v[50:51] op_sel_hi:[0,1]
	s_waitcnt lgkmcnt(13)
	v_pk_mul_f32 v[52:53], v[146:147], v[104:105]
	v_lshl_add_u64 v[66:67], v[66:67], 0, s[76:77]
	v_pk_fma_f32 v[94:95], v[60:61], v[0:1], v[52:53] op_sel_hi:[1,0,1] neg_lo:[0,0,1] neg_hi:[0,0,1]
	v_pk_mul_f32 v[52:53], v[146:147], v[102:103]
	v_lshl_add_u64 v[88:89], v[68:69], 2, s[42:43]
	v_pk_fma_f32 v[100:101], v[58:59], v[0:1], v[52:53] op_sel_hi:[1,0,1] neg_lo:[0,0,1] neg_hi:[0,0,1]
	v_lshl_add_u64 v[86:87], v[68:69], 1, v[66:67]
	v_pk_fma_f32 v[50:51], v[100:101], v[100:101], v[50:51]
	v_mul_f32_e32 v52, v101, v101
	v_pk_add_f32 v[50:51], v[52:53], v[50:51] op_sel_hi:[0,1]
	v_pk_fma_f32 v[50:51], v[94:95], v[94:95], v[50:51]
	v_mul_f32_e32 v52, v95, v95
	v_pk_add_f32 v[50:51], v[52:53], v[50:51] op_sel_hi:[0,1]
	s_waitcnt lgkmcnt(12)
	v_pk_mul_f32 v[52:53], v[146:147], v[108:109]
	v_pk_fma_f32 v[60:61], v[64:65], v[0:1], v[52:53] op_sel_hi:[1,0,1] neg_lo:[0,0,1] neg_hi:[0,0,1]
	v_pk_mul_f32 v[52:53], v[146:147], v[106:107]
	s_nop 0
	v_pk_fma_f32 v[64:65], v[62:63], v[0:1], v[52:53] op_sel_hi:[1,0,1] neg_lo:[0,0,1] neg_hi:[0,0,1]
	s_nop 0
	v_pk_fma_f32 v[50:51], v[64:65], v[64:65], v[50:51]
	v_mul_f32_e32 v52, v65, v65
	v_pk_add_f32 v[50:51], v[52:53], v[50:51] op_sel_hi:[0,1]
	v_pk_fma_f32 v[50:51], v[60:61], v[60:61], v[50:51]
	v_mul_f32_e32 v52, v61, v61
	v_pk_add_f32 v[50:51], v[52:53], v[50:51] op_sel_hi:[0,1]
	s_waitcnt lgkmcnt(11)
	v_pk_mul_f32 v[52:53], v[146:147], v[112:113]
	s_nop 0
	v_pk_fma_f32 v[56:57], v[36:37], v[0:1], v[52:53] op_sel_hi:[1,0,1] neg_lo:[0,0,1] neg_hi:[0,0,1]
	v_pk_mul_f32 v[36:37], v[146:147], v[110:111]
	s_nop 0
	v_pk_fma_f32 v[62:63], v[34:35], v[0:1], v[36:37] op_sel_hi:[1,0,1] neg_lo:[0,0,1] neg_hi:[0,0,1]
	s_nop 0
	v_pk_fma_f32 v[34:35], v[62:63], v[62:63], v[50:51]
	v_mul_f32_e32 v36, v63, v63
	v_pk_add_f32 v[34:35], v[36:37], v[34:35] op_sel_hi:[0,1]
	v_pk_fma_f32 v[34:35], v[56:57], v[56:57], v[34:35]
	v_mul_f32_e32 v36, v57, v57
	v_pk_add_f32 v[34:35], v[36:37], v[34:35] op_sel_hi:[0,1]
	s_waitcnt lgkmcnt(10)
	v_pk_mul_f32 v[36:37], v[146:147], v[116:117]
	s_nop 0
	v_pk_fma_f32 v[52:53], v[40:41], v[0:1], v[36:37] op_sel_hi:[1,0,1] neg_lo:[0,0,1] neg_hi:[0,0,1]
	v_pk_mul_f32 v[36:37], v[146:147], v[114:115]
	s_nop 0
	v_pk_fma_f32 v[58:59], v[38:39], v[0:1], v[36:37] op_sel_hi:[1,0,1] neg_lo:[0,0,1] neg_hi:[0,0,1]
	s_nop 0
	v_pk_fma_f32 v[34:35], v[58:59], v[58:59], v[34:35]
	v_mul_f32_e32 v36, v59, v59
	v_pk_add_f32 v[34:35], v[36:37], v[34:35] op_sel_hi:[0,1]
	v_pk_fma_f32 v[34:35], v[52:53], v[52:53], v[34:35]
	v_mul_f32_e32 v36, v53, v53
	v_pk_add_f32 v[34:35], v[36:37], v[34:35] op_sel_hi:[0,1]
	s_waitcnt lgkmcnt(9)
	v_pk_mul_f32 v[36:37], v[146:147], v[120:121]
	s_nop 0
	v_pk_fma_f32 v[50:51], v[44:45], v[0:1], v[36:37] op_sel_hi:[1,0,1] neg_lo:[0,0,1] neg_hi:[0,0,1]
	v_pk_mul_f32 v[36:37], v[146:147], v[118:119]
	s_nop 0
	v_pk_fma_f32 v[54:55], v[42:43], v[0:1], v[36:37] op_sel_hi:[1,0,1] neg_lo:[0,0,1] neg_hi:[0,0,1]
	s_nop 0
	v_pk_fma_f32 v[34:35], v[54:55], v[54:55], v[34:35]
	v_mul_f32_e32 v36, v55, v55
	v_pk_add_f32 v[34:35], v[36:37], v[34:35] op_sel_hi:[0,1]
	v_pk_fma_f32 v[34:35], v[50:51], v[50:51], v[34:35]
	v_mul_f32_e32 v36, v51, v51
	v_pk_add_f32 v[34:35], v[36:37], v[34:35] op_sel_hi:[0,1]
	s_waitcnt lgkmcnt(8)
; __device__ __forceinline__ void diff_unit(ALDS unsigned char* ring, const int wid, int lane, const bf16_t* qkv, bf16_t* ymix, const int u, const float lam, const float post, const float* subg, const bool pre, const int u_next) {
;     ...
;             for (int rq = 0; rq < 4; ++rq) { const f32x4 o2 = X[(db * 4 + rq) * 64 + lane];
; #pragma unroll
;                 for (int e = 0; e < 4; ++e) { const float d = o[db][4 * rq + e] * inv - lam * o2[e]; o[db][4 * rq + e] = d; ss += d * d; } }
	v_pk_mul_f32 v[36:37], v[146:147], v[124:125]
	s_nop 0
	v_pk_fma_f32 v[42:43], v[48:49], v[0:1], v[36:37] op_sel_hi:[1,0,1] neg_lo:[0,0,1] neg_hi:[0,0,1]
	v_pk_mul_f32 v[36:37], v[146:147], v[122:123]
	s_nop 0
	v_pk_fma_f32 v[46:47], v[46:47], v[0:1], v[36:37] op_sel_hi:[1,0,1] neg_lo:[0,0,1] neg_hi:[0,0,1]
	s_nop 0
	v_pk_fma_f32 v[34:35], v[46:47], v[46:47], v[34:35]
	v_mul_f32_e32 v36, v47, v47
	v_pk_add_f32 v[34:35], v[36:37], v[34:35] op_sel_hi:[0,1]
	v_pk_fma_f32 v[34:35], v[42:43], v[42:43], v[34:35]
	v_mul_f32_e32 v36, v43, v43
	v_pk_add_f32 v[34:35], v[36:37], v[34:35] op_sel_hi:[0,1]
	s_waitcnt lgkmcnt(7)
	v_pk_mul_f32 v[36:37], v[146:147], v[128:129]
	s_nop 0
	v_pk_fma_f32 v[38:39], v[20:21], v[0:1], v[36:37] op_sel_hi:[1,0,1] neg_lo:[0,0,1] neg_hi:[0,0,1]
	v_pk_mul_f32 v[20:21], v[146:147], v[126:127]
	s_nop 0
	v_pk_fma_f32 v[44:45], v[18:19], v[0:1], v[20:21] op_sel_hi:[1,0,1] neg_lo:[0,0,1] neg_hi:[0,0,1]
	s_nop 0
	v_pk_fma_f32 v[18:19], v[44:45], v[44:45], v[34:35]
	v_mul_f32_e32 v20, v45, v45
	v_pk_add_f32 v[18:19], v[20:21], v[18:19] op_sel_hi:[0,1]
	v_pk_fma_f32 v[18:19], v[38:39], v[38:39], v[18:19]
	v_mul_f32_e32 v20, v39, v39
	v_pk_add_f32 v[18:19], v[20:21], v[18:19] op_sel_hi:[0,1]
	s_waitcnt lgkmcnt(6)
	v_pk_mul_f32 v[20:21], v[146:147], v[132:133]
	s_nop 0
	v_pk_fma_f32 v[34:35], v[24:25], v[0:1], v[20:21] op_sel_hi:[1,0,1] neg_lo:[0,0,1] neg_hi:[0,0,1]
	v_pk_mul_f32 v[20:21], v[146:147], v[130:131]
	s_nop 0
	v_pk_fma_f32 v[40:41], v[22:23], v[0:1], v[20:21] op_sel_hi:[1,0,1] neg_lo:[0,0,1] neg_hi:[0,0,1]
	s_nop 0
	v_pk_fma_f32 v[18:19], v[40:41], v[40:41], v[18:19]
	v_mul_f32_e32 v20, v41, v41
	v_pk_add_f32 v[18:19], v[20:21], v[18:19] op_sel_hi:[0,1]
	v_pk_fma_f32 v[18:19], v[34:35], v[34:35], v[18:19]
	v_mul_f32_e32 v20, v35, v35
	v_pk_add_f32 v[18:19], v[20:21], v[18:19] op_sel_hi:[0,1]
	s_waitcnt lgkmcnt(5)
	v_pk_mul_f32 v[20:21], v[146:147], v[136:137]
	s_nop 0
	v_pk_fma_f32 v[28:29], v[28:29], v[0:1], v[20:21] op_sel_hi:[1,0,1] neg_lo:[0,0,1] neg_hi:[0,0,1]
	v_pk_mul_f32 v[20:21], v[146:147], v[134:135]
	s_nop 0
	v_pk_fma_f32 v[36:37], v[26:27], v[0:1], v[20:21] op_sel_hi:[1,0,1] neg_lo:[0,0,1] neg_hi:[0,0,1]
	s_nop 0
	v_pk_fma_f32 v[18:19], v[36:37], v[36:37], v[18:19]
	v_mul_f32_e32 v20, v37, v37
	v_pk_add_f32 v[18:19], v[20:21], v[18:19] op_sel_hi:[0,1]
	v_pk_fma_f32 v[18:19], v[28:29], v[28:29], v[18:19]
	v_mul_f32_e32 v20, v29, v29
	v_pk_add_f32 v[18:19], v[20:21], v[18:19] op_sel_hi:[0,1]
	s_waitcnt lgkmcnt(4)
	v_pk_mul_f32 v[20:21], v[146:147], v[140:141]
	s_nop 0
	v_pk_fma_f32 v[22:23], v[32:33], v[0:1], v[20:21] op_sel_hi:[1,0,1] neg_lo:[0,0,1] neg_hi:[0,0,1]
	v_pk_mul_f32 v[20:21], v[146:147], v[138:139]
	s_nop 0
	v_pk_fma_f32 v[26:27], v[30:31], v[0:1], v[20:21] op_sel_hi:[1,0,1] neg_lo:[0,0,1] neg_hi:[0,0,1]
	s_nop 0
	v_pk_fma_f32 v[18:19], v[26:27], v[26:27], v[18:19]
	v_mul_f32_e32 v20, v27, v27
	v_pk_add_f32 v[18:19], v[20:21], v[18:19] op_sel_hi:[0,1]
	v_pk_fma_f32 v[18:19], v[22:23], v[22:23], v[18:19]
	v_mul_f32_e32 v20, v23, v23
	v_pk_add_f32 v[20:21], v[20:21], v[18:19] op_sel_hi:[0,1]
	s_waitcnt lgkmcnt(3)
	v_pk_mul_f32 v[18:19], v[146:147], v[84:85]
	s_nop 0
	v_pk_fma_f32 v[18:19], v[4:5], v[0:1], v[18:19] op_sel_hi:[1,0,1] neg_lo:[0,0,1] neg_hi:[0,0,1]
	v_pk_mul_f32 v[4:5], v[146:147], v[82:83]
	s_nop 0
	v_pk_fma_f32 v[24:25], v[2:3], v[0:1], v[4:5] op_sel_hi:[1,0,1] neg_lo:[0,0,1] neg_hi:[0,0,1]
	s_nop 0
	v_pk_fma_f32 v[2:3], v[24:25], v[24:25], v[20:21]
	v_mul_f32_e32 v4, v25, v25
	v_pk_add_f32 v[2:3], v[4:5], v[2:3] op_sel_hi:[0,1]
	v_pk_fma_f32 v[2:3], v[18:19], v[18:19], v[2:3]
	v_mul_f32_e32 v4, v19, v19
	v_pk_add_f32 v[2:3], v[4:5], v[2:3] op_sel_hi:[0,1]
	s_waitcnt lgkmcnt(2)
	v_pk_mul_f32 v[4:5], v[146:147], v[80:81]
	s_nop 0
	v_pk_fma_f32 v[8:9], v[8:9], v[0:1], v[4:5] op_sel_hi:[1,0,1] neg_lo:[0,0,1] neg_hi:[0,0,1]
	v_pk_mul_f32 v[4:5], v[146:147], v[78:79]
	s_nop 0
	v_pk_fma_f32 v[20:21], v[6:7], v[0:1], v[4:5] op_sel_hi:[1,0,1] neg_lo:[0,0,1] neg_hi:[0,0,1]
	s_waitcnt lgkmcnt(1)
	v_pk_mul_f32 v[6:7], v[146:147], v[74:75]
	v_pk_fma_f32 v[2:3], v[20:21], v[20:21], v[2:3]
	v_mul_f32_e32 v4, v21, v21
	v_pk_add_f32 v[2:3], v[4:5], v[2:3] op_sel_hi:[0,1]
	v_pk_fma_f32 v[2:3], v[8:9], v[8:9], v[2:3]
	v_mul_f32_e32 v4, v9, v9
	v_pk_add_f32 v[2:3], v[4:5], v[2:3] op_sel_hi:[0,1]
	v_pk_fma_f32 v[10:11], v[10:11], v[0:1], v[6:7] op_sel_hi:[1,0,1] neg_lo:[0,0,1] neg_hi:[0,0,1]
	v_pk_mul_f32 v[4:5], v[146:147], v[76:77]
	v_pk_fma_f32 v[2:3], v[10:11], v[10:11], v[2:3]
	v_mul_f32_e32 v6, v11, v11
	v_pk_fma_f32 v[4:5], v[12:13], v[0:1], v[4:5] op_sel_hi:[1,0,1] neg_lo:[0,0,1] neg_hi:[0,0,1]
	v_pk_add_f32 v[2:3], v[6:7], v[2:3] op_sel_hi:[0,1]
	v_pk_fma_f32 v[2:3], v[4:5], v[4:5], v[2:3]
	v_mul_f32_e32 v6, v5, v5
	v_pk_add_f32 v[12:13], v[6:7], v[2:3] op_sel_hi:[0,1]
	s_waitcnt lgkmcnt(0)
; __device__ __forceinline__ unsigned cvtpk(float lo, float hi) { f32x2_t v = {lo, hi}; bf16x2_t b = __builtin_convertvector(v, bf16x2_t); return __builtin_bit_cast(unsigned, b); }
; __device__ __forceinline__ float halfswap_sum(float v) { auto rr = __builtin_amdgcn_permlane32_swap(__float_as_uint(v), __float_as_uint(v), false, false); return __uint_as_float(rr[0]) + __uint_as_float(rr[1]); }
; __device__ __forceinline__ void diff_unit(ALDS unsigned char* ring, const int wid, int lane, const bf16_t* qkv, bf16_t* ymix, const int u, const float lam, const float post, const float* subg, const bool pre, const int u_next) {
;     ...
;         ss = halfswap_sum(ss);
;         const float rs = rsqrtf(ss * (1.0f / 128.0f) + 1e-5f) * post;
;         bf16_t* orow = ymix + (rowbase + q0 + r32) * 1024 + h * 128 + 4 * hi;
; #pragma unroll
;         for (int db = 0; db < 4; ++db)
; #pragma unroll
;             for (int rq = 0; rq < 4; ++rq) { const f32x4 gv = *(const f32x4*)(subg + 32 * db + 8 * rq + 4 * hi);
;                 u32x2 w; w.x = cvtpk(o[db][4 * rq] * rs * gv[0], o[db][4 * rq + 1] * rs * gv[1]); w.y = cvtpk(o[db][4 * rq + 2] * rs * gv[2], o[db][4 * rq + 3] * rs * gv[3]);
;                 *(u32x2*)(orow + 32 * db + 8 * rq) = w; }
	v_pk_mul_f32 v[6:7], v[146:147], v[70:71]
	v_pk_mul_f32 v[2:3], v[146:147], v[72:73]
	v_pk_fma_f32 v[6:7], v[14:15], v[0:1], v[6:7] op_sel_hi:[1,0,1] neg_lo:[0,0,1] neg_hi:[0,0,1]
	v_pk_fma_f32 v[2:3], v[16:17], v[0:1], v[2:3] op_sel_hi:[1,0,1] neg_lo:[0,0,1] neg_hi:[0,0,1]
	v_pk_fma_f32 v[12:13], v[6:7], v[6:7], v[12:13]
	v_mul_f32_e32 v0, v7, v7
	v_pk_add_f32 v[12:13], v[0:1], v[12:13] op_sel_hi:[0,1]
	v_pk_fma_f32 v[12:13], v[2:3], v[2:3], v[12:13]
	v_mul_f32_e32 v0, v3, v3
	v_pk_add_f32 v[12:13], v[0:1], v[12:13] op_sel_hi:[0,1]
	v_mov_b32_e32 v0, v12
	s_nop 1
	v_permlane32_swap_b32_e32 v12, v0
	v_add_f32_e32 v0, v12, v0
	v_mov_b32_e32 v12, 0x3727c5ac
	v_fmamk_f32 v0, v0, 0x3c000000, v12
	v_cmp_gt_f32_e32 vcc, s29, v0
	v_mul_f32_e32 v12, 0x4b800000, v0
	s_nop 0
	v_cndmask_b32_e32 v0, v0, v12, vcc
	v_rsq_f32_e32 v0, v0
	s_nop 0
	v_mul_f32_e32 v12, 0x45800000, v0
	v_cndmask_b32_e32 v0, v0, v12, vcc
	v_mul_f32_e32 v0, v148, v0
	v_pk_mul_f32 v[12:13], v[92:93], v[0:1] op_sel_hi:[1,0]
	v_pk_mul_f32 v[14:15], v[90:91], v[0:1] op_sel_hi:[1,0]
	v_pk_mul_f32 v[12:13], v[178:179], v[12:13]
	v_pk_mul_f32 v[14:15], v[180:181], v[14:15]
	v_cvt_pk_bf16_f32 v12, v12, v13
	v_cvt_pk_bf16_f32 v13, v14, v15
	global_store_dwordx2 v[86:87], v[12:13], off
	v_pk_mul_f32 v[16:17], v[98:99], v[0:1] op_sel_hi:[1,0]
	v_pk_mul_f32 v[8:9], v[8:9], v[0:1] op_sel_hi:[1,0]
	v_pk_mul_f32 v[4:5], v[4:5], v[0:1] op_sel_hi:[1,0]
	v_pk_mul_f32 v[2:3], v[2:3], v[0:1] op_sel_hi:[1,0]
	v_pk_mul_f32 v[12:13], v[182:183], v[16:17]
	v_pk_mul_f32 v[16:17], v[96:97], v[0:1] op_sel_hi:[1,0]
	v_cvt_pk_bf16_f32 v12, v12, v13
	v_pk_mul_f32 v[14:15], v[184:185], v[16:17]
	v_pk_mul_f32 v[16:17], v[100:101], v[0:1] op_sel_hi:[1,0]
	v_cvt_pk_bf16_f32 v13, v14, v15
	global_store_dwordx2 v[86:87], v[12:13], off offset:16
	v_pk_mul_f32 v[12:13], v[186:187], v[16:17]
	v_pk_mul_f32 v[16:17], v[94:95], v[0:1] op_sel_hi:[1,0]
	v_cvt_pk_bf16_f32 v12, v12, v13
	v_pk_mul_f32 v[14:15], v[188:189], v[16:17]
	v_pk_mul_f32 v[16:17], v[64:65], v[0:1] op_sel_hi:[1,0]
	v_cvt_pk_bf16_f32 v13, v14, v15
	global_store_dwordx2 v[86:87], v[12:13], off offset:32
	v_pk_mul_f32 v[12:13], v[190:191], v[16:17]
	v_pk_mul_f32 v[16:17], v[60:61], v[0:1] op_sel_hi:[1,0]
	v_cvt_pk_bf16_f32 v12, v12, v13
	v_pk_mul_f32 v[14:15], v[192:193], v[16:17]
	v_pk_mul_f32 v[16:17], v[62:63], v[0:1] op_sel_hi:[1,0]
	v_cvt_pk_bf16_f32 v13, v14, v15
	global_store_dwordx2 v[86:87], v[12:13], off offset:48
	v_pk_mul_f32 v[12:13], v[194:195], v[16:17]
	v_pk_mul_f32 v[16:17], v[56:57], v[0:1] op_sel_hi:[1,0]
	v_cvt_pk_bf16_f32 v12, v12, v13
	v_pk_mul_f32 v[14:15], v[196:197], v[16:17]
	v_pk_mul_f32 v[16:17], v[58:59], v[0:1] op_sel_hi:[1,0]
	v_cvt_pk_bf16_f32 v13, v14, v15
	global_store_dwordx2 v[86:87], v[12:13], off offset:64
	v_pk_mul_f32 v[12:13], v[198:199], v[16:17]
	v_pk_mul_f32 v[16:17], v[52:53], v[0:1] op_sel_hi:[1,0]
	v_cvt_pk_bf16_f32 v12, v12, v13
	v_pk_mul_f32 v[14:15], v[200:201], v[16:17]
	v_pk_mul_f32 v[16:17], v[54:55], v[0:1] op_sel_hi:[1,0]
	v_cvt_pk_bf16_f32 v13, v14, v15
	global_store_dwordx2 v[86:87], v[12:13], off offset:80
	v_pk_mul_f32 v[12:13], v[16:17], v[202:203]
	v_pk_mul_f32 v[16:17], v[50:51], v[0:1] op_sel_hi:[1,0]
	v_cvt_pk_bf16_f32 v12, v12, v13
	v_pk_mul_f32 v[14:15], v[16:17], v[204:205]
	v_pk_mul_f32 v[16:17], v[46:47], v[0:1] op_sel_hi:[1,0]
	v_cvt_pk_bf16_f32 v13, v14, v15
	global_store_dwordx2 v[86:87], v[12:13], off offset:96
	v_pk_mul_f32 v[12:13], v[16:17], v[210:211]
	v_pk_mul_f32 v[16:17], v[42:43], v[0:1] op_sel_hi:[1,0]
	v_cvt_pk_bf16_f32 v12, v12, v13
	v_pk_mul_f32 v[14:15], v[16:17], v[212:213]
	v_pk_mul_f32 v[16:17], v[44:45], v[0:1] op_sel_hi:[1,0]
	v_cvt_pk_bf16_f32 v13, v14, v15
	global_store_dwordx2 v[86:87], v[12:13], off offset:112
	v_pk_mul_f32 v[12:13], v[16:17], v[214:215]
	v_pk_mul_f32 v[16:17], v[38:39], v[0:1] op_sel_hi:[1,0]
	v_cvt_pk_bf16_f32 v12, v12, v13
	v_pk_mul_f32 v[14:15], v[16:17], v[216:217]
	v_pk_mul_f32 v[16:17], v[40:41], v[0:1] op_sel_hi:[1,0]
	v_cvt_pk_bf16_f32 v13, v14, v15
	global_store_dwordx2 v[86:87], v[12:13], off offset:128
	v_pk_mul_f32 v[12:13], v[16:17], v[218:219]
	v_pk_mul_f32 v[16:17], v[34:35], v[0:1] op_sel_hi:[1,0]
	v_cvt_pk_bf16_f32 v12, v12, v13
	v_pk_mul_f32 v[14:15], v[16:17], v[220:221]
	v_pk_mul_f32 v[16:17], v[36:37], v[0:1] op_sel_hi:[1,0]
	v_cvt_pk_bf16_f32 v13, v14, v15
	global_store_dwordx2 v[86:87], v[12:13], off offset:144
	v_pk_mul_f32 v[12:13], v[16:17], v[222:223]
	v_pk_mul_f32 v[16:17], v[28:29], v[0:1] op_sel_hi:[1,0]
	v_cvt_pk_bf16_f32 v12, v12, v13
	v_pk_mul_f32 v[14:15], v[16:17], v[224:225]
	v_pk_mul_f32 v[16:17], v[26:27], v[0:1] op_sel_hi:[1,0]
	v_cvt_pk_bf16_f32 v13, v14, v15
	global_store_dwordx2 v[86:87], v[12:13], off offset:160
	v_pk_mul_f32 v[12:13], v[16:17], v[226:227]
	v_pk_mul_f32 v[16:17], v[22:23], v[0:1] op_sel_hi:[1,0]
	v_cvt_pk_bf16_f32 v12, v12, v13
	v_pk_mul_f32 v[14:15], v[16:17], v[228:229]
	v_pk_mul_f32 v[16:17], v[24:25], v[0:1] op_sel_hi:[1,0]
	v_cvt_pk_bf16_f32 v13, v14, v15
	global_store_dwordx2 v[86:87], v[12:13], off offset:176
	v_pk_mul_f32 v[12:13], v[16:17], v[232:233]
	v_pk_mul_f32 v[16:17], v[18:19], v[0:1] op_sel_hi:[1,0]
	v_cvt_pk_bf16_f32 v12, v12, v13
	v_pk_mul_f32 v[14:15], v[16:17], v[234:235]
	v_pk_mul_f32 v[16:17], v[20:21], v[0:1] op_sel_hi:[1,0]
	v_cvt_pk_bf16_f32 v13, v14, v15
	global_store_dwordx2 v[86:87], v[12:13], off offset:192
	v_pk_mul_f32 v[12:13], v[16:17], v[236:237]
	v_pk_mul_f32 v[8:9], v[8:9], v[238:239]
	v_cvt_pk_bf16_f32 v12, v12, v13
	v_cvt_pk_bf16_f32 v13, v8, v9
	global_store_dwordx2 v[86:87], v[12:13], off offset:208
	v_pk_mul_f32 v[8:9], v[10:11], v[0:1] op_sel_hi:[1,0]
	v_pk_mul_f32 v[4:5], v[4:5], v[242:243]
	v_pk_mul_f32 v[8:9], v[8:9], v[240:241]
	s_nop 0
	v_cvt_pk_bf16_f32 v8, v8, v9
	v_cvt_pk_bf16_f32 v9, v4, v5
	global_store_dwordx2 v[86:87], v[8:9], off offset:224
	v_pk_mul_f32 v[4:5], v[6:7], v[0:1] op_sel_hi:[1,0]
	v_pk_mul_f32 v[2:3], v[2:3], v[246:247]
	v_pk_mul_f32 v[4:5], v[4:5], v[244:245]
	s_nop 0
	v_cvt_pk_bf16_f32 v4, v4, v5
	v_cvt_pk_bf16_f32 v5, v2, v3
	global_store_dwordx2 v[86:87], v[4:5], off offset:240
	s_branch .LBB0_765
